# FoX item epilogue: the 8 output-gate loads issued together (one wait), result stores no longer drained between gate loads
# speedup vs baseline: 1.0088x; 1.0088x over previous
.LBB0_241:
	s_mulk_i32 s50, 0x2080
	v_add_u32_e32 v33, s50, v102
	v_mov_b64_e32 v[34:35], s[56:57]
	v_mad_i64_i32 v[34:35], s[0:1], v33, s13, v[34:35]
	s_mov_b32 s93, s17
	v_lshl_add_u64 v[36:37], v[34:35], 0, s[92:93]
	v_mov_b32_e32 v107, v179
	v_lshl_add_u64 v[34:35], v[106:107], 1, v[36:37]
	global_load_dwordx2 v[38:39], v[34:35], off offset:3088
	global_load_dwordx2 v[158:159], v[34:35], off offset:3152
	global_load_dwordx2 v[160:161], v[34:35], off offset:3104
	global_load_dwordx2 v[162:163], v[34:35], off offset:3168
	global_load_dwordx2 v[164:165], v[34:35], off offset:3120
	global_load_dwordx2 v[166:167], v[34:35], off offset:3184
	global_load_dwordx2 v[168:169], v[34:35], off offset:3136
	global_load_dwordx2 v[170:171], v[34:35], off offset:3200
	ds_bpermute_b32 v32, v103, v109
	v_cmp_lt_i32_e32 vcc, s46, v102
	v_mov_b32_e32 v101, v179
	s_mov_b32 s92, 0x8200
	s_mov_b64 s[50:51], s[68:69]
	s_waitcnt lgkmcnt(0)
	v_add_f32_e32 v32, v109, v32
	v_rcp_f32_e32 v32, v32
	s_movk_i32 s44, 0x2000
	s_mov_b32 s52, 0x800000
	s_waitcnt vmcnt(0)
	v_lshlrev_b32_e32 v33, 16, v38
	v_and_b32_e32 v40, 0xffff0000, v38
	v_mul_f32_e32 v38, 0xbfb8aa3b, v33
	v_exp_f32_e32 v38, v38
	v_lshlrev_b32_e32 v41, 16, v39
	v_and_b32_e32 v42, 0xffff0000, v39
	v_add_f32_e32 v38, 1.0, v38
	v_rcp_f32_e32 v39, v38
	v_mov_b32_e32 v38, v16
	v_mul_f32_e32 v16, 0xbfb8aa3b, v40
	v_exp_f32_e32 v16, v16
	v_pk_mul_f32 v[38:39], v[38:39], v[32:33]
	v_mov_b32_e32 v33, v40
	v_mul_f32_e32 v43, v38, v39
	v_add_f32_e32 v16, 1.0, v16
	v_rcp_f32_e32 v39, v16
	v_mov_b32_e32 v38, v17
	v_pk_mul_f32 v[16:17], v[38:39], v[32:33]
	s_nop 0
	v_mul_f32_e32 v38, v16, v17
	v_mul_f32_e32 v16, 0xbfb8aa3b, v41
	v_exp_f32_e32 v16, v16
	v_mov_b32_e32 v33, v41
	v_add_f32_e32 v16, 1.0, v16
	v_rcp_f32_e32 v17, v16
	v_mov_b32_e32 v16, v18
	v_pk_mul_f32 v[16:17], v[16:17], v[32:33]
	s_nop 0
	v_mul_f32_e32 v18, v16, v17
	v_mul_f32_e32 v16, 0xbfb8aa3b, v42
	v_exp_f32_e32 v16, v16
	v_mov_b32_e32 v33, v42
	v_add_f32_e32 v16, 1.0, v16
	v_rcp_f32_e32 v17, v16
	v_mov_b32_e32 v16, v19
	v_cvt_pk_bf16_f32 v19, v43, v38
	v_pk_mul_f32 v[16:17], v[16:17], v[32:33]
	s_nop 0
	v_mul_f32_e32 v16, v16, v17
	v_cvt_pk_bf16_f32 v16, v18, v16
	s_nop 0
	v_cndmask_b32_e32 v17, 0, v16, vcc
	v_cndmask_b32_e32 v16, 0, v19, vcc
	global_store_dwordx2 v[34:35], v[16:17], off
	v_mov_b32_e32 v16, v158
	v_mov_b32_e32 v17, v159
	v_lshlrev_b32_e32 v33, 16, v16
	v_and_b32_e32 v18, 0xffff0000, v16
	v_mul_f32_e32 v16, 0xbfb8aa3b, v33
	v_exp_f32_e32 v16, v16
	v_lshlrev_b32_e32 v19, 16, v17
	v_and_b32_e32 v38, 0xffff0000, v17
	v_add_f32_e32 v16, 1.0, v16
	v_rcp_f32_e32 v17, v16
	v_mov_b32_e32 v16, v0
	v_mul_f32_e32 v0, 0xbfb8aa3b, v18
	v_exp_f32_e32 v0, v0
	v_pk_mul_f32 v[16:17], v[16:17], v[32:33]
	v_mov_b32_e32 v33, v18
	v_mul_f32_e32 v39, v16, v17
	v_add_f32_e32 v0, 1.0, v0
	v_rcp_f32_e32 v17, v0
	v_mov_b32_e32 v16, v1
	v_pk_mul_f32 v[0:1], v[16:17], v[32:33]
	s_nop 0
	v_mul_f32_e32 v16, v0, v1
	v_mul_f32_e32 v0, 0xbfb8aa3b, v19
	v_exp_f32_e32 v0, v0
	v_mov_b32_e32 v33, v19
	v_add_f32_e32 v0, 1.0, v0
	v_rcp_f32_e32 v1, v0
	v_mov_b32_e32 v0, v2
	v_pk_mul_f32 v[0:1], v[0:1], v[32:33]
	s_nop 0
	v_mul_f32_e32 v2, v0, v1
	v_mul_f32_e32 v0, 0xbfb8aa3b, v38
	v_exp_f32_e32 v0, v0
	v_mov_b32_e32 v33, v38
	v_add_f32_e32 v0, 1.0, v0
	v_rcp_f32_e32 v1, v0
	v_mov_b32_e32 v0, v3
	v_cvt_pk_bf16_f32 v3, v39, v16
	v_pk_mul_f32 v[0:1], v[0:1], v[32:33]
	s_nop 0
	v_mul_f32_e32 v0, v0, v1
	v_cvt_pk_bf16_f32 v0, v2, v0
	s_nop 0
	v_cndmask_b32_e32 v1, 0, v0, vcc
	v_cndmask_b32_e32 v0, 0, v3, vcc
	global_store_dwordx2 v[34:35], v[0:1], off offset:64
	v_mov_b32_e32 v0, v160
	v_mov_b32_e32 v1, v161
	v_lshlrev_b32_e32 v33, 16, v0
	v_and_b32_e32 v2, 0xffff0000, v0
	v_mul_f32_e32 v0, 0xbfb8aa3b, v33
	v_exp_f32_e32 v0, v0
	v_lshlrev_b32_e32 v3, 16, v1
	v_and_b32_e32 v16, 0xffff0000, v1
	v_add_f32_e32 v0, 1.0, v0
	v_rcp_f32_e32 v1, v0
	v_mov_b32_e32 v0, v20
	v_pk_mul_f32 v[0:1], v[0:1], v[32:33]
	s_nop 0
	v_mul_f32_e32 v17, v0, v1
	v_mul_f32_e32 v0, 0xbfb8aa3b, v2
	v_exp_f32_e32 v0, v0
	v_mov_b32_e32 v33, v2
	v_add_f32_e32 v0, 1.0, v0
	v_rcp_f32_e32 v1, v0
	v_mov_b32_e32 v0, v21
	v_pk_mul_f32 v[0:1], v[0:1], v[32:33]
	s_nop 0
	v_mul_f32_e32 v2, v0, v1
	v_mul_f32_e32 v0, 0xbfb8aa3b, v3
	v_exp_f32_e32 v0, v0
	v_mov_b32_e32 v33, v3
	v_cvt_pk_bf16_f32 v2, v17, v2
	v_add_f32_e32 v0, 1.0, v0
	v_rcp_f32_e32 v1, v0
	v_mov_b32_e32 v0, v22
	v_pk_mul_f32 v[0:1], v[0:1], v[32:33]
	s_nop 0
	v_mul_f32_e32 v3, v0, v1
	v_mul_f32_e32 v0, 0xbfb8aa3b, v16
	v_exp_f32_e32 v0, v0
	v_mov_b32_e32 v33, v16
	v_add_f32_e32 v0, 1.0, v0
	v_rcp_f32_e32 v1, v0
	v_mov_b32_e32 v0, v23
	v_pk_mul_f32 v[0:1], v[0:1], v[32:33]
	s_nop 0
	v_mul_f32_e32 v0, v0, v1
	v_cvt_pk_bf16_f32 v0, v3, v0
	s_nop 0
	v_cndmask_b32_e32 v1, 0, v0, vcc
	v_cndmask_b32_e32 v0, 0, v2, vcc
	global_store_dwordx2 v[34:35], v[0:1], off offset:16
	v_mov_b32_e32 v0, v162
	v_mov_b32_e32 v1, v163
	v_lshlrev_b32_e32 v33, 16, v0
	v_and_b32_e32 v2, 0xffff0000, v0
	v_mul_f32_e32 v0, 0xbfb8aa3b, v33
	v_exp_f32_e32 v0, v0
	v_lshlrev_b32_e32 v3, 16, v1
	v_and_b32_e32 v16, 0xffff0000, v1
	v_add_f32_e32 v0, 1.0, v0
	v_rcp_f32_e32 v1, v0
	v_mov_b32_e32 v0, v4
	v_pk_mul_f32 v[0:1], v[0:1], v[32:33]
	s_nop 0
	v_mul_f32_e32 v4, v0, v1
	v_mul_f32_e32 v0, 0xbfb8aa3b, v2
	v_exp_f32_e32 v0, v0
	v_mov_b32_e32 v33, v2
	v_add_f32_e32 v0, 1.0, v0
	v_rcp_f32_e32 v1, v0
	v_mov_b32_e32 v0, v5
	v_pk_mul_f32 v[0:1], v[0:1], v[32:33]
	s_nop 0
	v_mul_f32_e32 v2, v0, v1
	v_mul_f32_e32 v0, 0xbfb8aa3b, v3
	v_exp_f32_e32 v0, v0
	v_mov_b32_e32 v33, v3
	v_cvt_pk_bf16_f32 v2, v4, v2
	v_add_f32_e32 v0, 1.0, v0
	v_rcp_f32_e32 v1, v0
	v_mov_b32_e32 v0, v6
	v_pk_mul_f32 v[0:1], v[0:1], v[32:33]
	s_nop 0
	v_mul_f32_e32 v3, v0, v1
	v_mul_f32_e32 v0, 0xbfb8aa3b, v16
	v_exp_f32_e32 v0, v0
	v_mov_b32_e32 v33, v16
	v_add_f32_e32 v0, 1.0, v0
	v_rcp_f32_e32 v1, v0
	v_mov_b32_e32 v0, v7
	v_pk_mul_f32 v[0:1], v[0:1], v[32:33]
	s_nop 0
	v_mul_f32_e32 v0, v0, v1
	v_cvt_pk_bf16_f32 v0, v3, v0
	s_nop 0
	v_cndmask_b32_e32 v1, 0, v0, vcc
	v_cndmask_b32_e32 v0, 0, v2, vcc
	global_store_dwordx2 v[34:35], v[0:1], off offset:80
	v_lshl_add_u64 v[0:1], v[100:101], 1, v[36:37]
	v_mov_b32_e32 v2, v164
	v_mov_b32_e32 v3, v165
	v_lshlrev_b32_e32 v33, 16, v2
	v_and_b32_e32 v4, 0xffff0000, v2
	v_mul_f32_e32 v2, 0xbfb8aa3b, v33
	v_exp_f32_e32 v2, v2
	v_lshlrev_b32_e32 v5, 16, v3
	v_and_b32_e32 v6, 0xffff0000, v3
	v_add_f32_e32 v2, 1.0, v2
	v_rcp_f32_e32 v3, v2
	v_mov_b32_e32 v2, v24
	v_pk_mul_f32 v[2:3], v[2:3], v[32:33]
	s_nop 0
	v_mul_f32_e32 v7, v2, v3
	v_mul_f32_e32 v2, 0xbfb8aa3b, v4
	v_exp_f32_e32 v2, v2
	v_mov_b32_e32 v33, v4
	v_add_f32_e32 v2, 1.0, v2
	v_rcp_f32_e32 v3, v2
	v_mov_b32_e32 v2, v25
	v_pk_mul_f32 v[2:3], v[2:3], v[32:33]
	s_nop 0
	v_mul_f32_e32 v4, v2, v3
	v_mul_f32_e32 v2, 0xbfb8aa3b, v5
	v_exp_f32_e32 v2, v2
	v_mov_b32_e32 v33, v5
	v_cvt_pk_bf16_f32 v4, v7, v4
	v_add_f32_e32 v2, 1.0, v2
	v_rcp_f32_e32 v3, v2
	v_mov_b32_e32 v2, v26
	v_pk_mul_f32 v[2:3], v[2:3], v[32:33]
	s_nop 0
	v_mul_f32_e32 v5, v2, v3
	v_mul_f32_e32 v2, 0xbfb8aa3b, v6
	v_exp_f32_e32 v2, v2
	v_mov_b32_e32 v33, v6
	v_add_f32_e32 v2, 1.0, v2
	v_rcp_f32_e32 v3, v2
	v_mov_b32_e32 v2, v27
	v_pk_mul_f32 v[2:3], v[2:3], v[32:33]
	s_nop 0
	v_mul_f32_e32 v2, v2, v3
	v_cvt_pk_bf16_f32 v2, v5, v2
	s_nop 0
	v_cndmask_b32_e32 v3, 0, v2, vcc
	v_cndmask_b32_e32 v2, 0, v4, vcc
	global_store_dwordx2 v[0:1], v[2:3], off
	v_mov_b32_e32 v0, v166
	v_mov_b32_e32 v1, v167
	v_lshlrev_b32_e32 v33, 16, v0
	v_and_b32_e32 v2, 0xffff0000, v0
	v_mul_f32_e32 v0, 0xbfb8aa3b, v33
	v_exp_f32_e32 v0, v0
	v_lshlrev_b32_e32 v3, 16, v1
	v_and_b32_e32 v4, 0xffff0000, v1
	v_add_f32_e32 v0, 1.0, v0
	v_rcp_f32_e32 v1, v0
	v_mov_b32_e32 v0, v8
	v_pk_mul_f32 v[0:1], v[0:1], v[32:33]
	s_nop 0
	v_mul_f32_e32 v5, v0, v1
	v_mul_f32_e32 v0, 0xbfb8aa3b, v2
	v_exp_f32_e32 v0, v0
	v_mov_b32_e32 v33, v2
	v_add_f32_e32 v0, 1.0, v0
	v_rcp_f32_e32 v1, v0
	v_mov_b32_e32 v0, v9
	v_pk_mul_f32 v[0:1], v[0:1], v[32:33]
	s_nop 0
	v_mul_f32_e32 v2, v0, v1
	v_mul_f32_e32 v0, 0xbfb8aa3b, v3
	v_exp_f32_e32 v0, v0
	v_mov_b32_e32 v33, v3
	v_cvt_pk_bf16_f32 v2, v5, v2
	v_add_f32_e32 v0, 1.0, v0
	v_rcp_f32_e32 v1, v0
	v_mov_b32_e32 v0, v10
	v_pk_mul_f32 v[0:1], v[0:1], v[32:33]
	s_nop 0
	v_mul_f32_e32 v3, v0, v1
	v_mul_f32_e32 v0, 0xbfb8aa3b, v4
	v_exp_f32_e32 v0, v0
	v_mov_b32_e32 v33, v4
	v_add_f32_e32 v0, 1.0, v0
	v_rcp_f32_e32 v1, v0
	v_mov_b32_e32 v0, v11
	v_pk_mul_f32 v[0:1], v[0:1], v[32:33]
	s_nop 0
	v_mul_f32_e32 v0, v0, v1
	v_cvt_pk_bf16_f32 v0, v3, v0
	s_nop 0
	v_cndmask_b32_e32 v1, 0, v0, vcc
	v_cndmask_b32_e32 v0, 0, v2, vcc
	global_store_dwordx2 v[34:35], v[0:1], off offset:96
	v_mov_b32_e32 v0, v168
	v_mov_b32_e32 v1, v169
	v_lshlrev_b32_e32 v33, 16, v0
	v_and_b32_e32 v2, 0xffff0000, v0
	v_mul_f32_e32 v0, 0xbfb8aa3b, v33
	v_exp_f32_e32 v0, v0
	v_lshlrev_b32_e32 v3, 16, v1
	v_and_b32_e32 v4, 0xffff0000, v1
	v_add_f32_e32 v0, 1.0, v0
	v_rcp_f32_e32 v1, v0
	v_mov_b32_e32 v0, v28
	v_pk_mul_f32 v[0:1], v[0:1], v[32:33]
	s_nop 0
	v_mul_f32_e32 v5, v0, v1
	v_mul_f32_e32 v0, 0xbfb8aa3b, v2
	v_exp_f32_e32 v0, v0
	v_mov_b32_e32 v33, v2
	v_add_f32_e32 v0, 1.0, v0
	v_rcp_f32_e32 v1, v0
	v_mov_b32_e32 v0, v29
	v_pk_mul_f32 v[0:1], v[0:1], v[32:33]
	s_nop 0
	v_mul_f32_e32 v2, v0, v1
	v_mul_f32_e32 v0, 0xbfb8aa3b, v3
	v_exp_f32_e32 v0, v0
	v_mov_b32_e32 v33, v3
	v_cvt_pk_bf16_f32 v2, v5, v2
	v_add_f32_e32 v0, 1.0, v0
	v_rcp_f32_e32 v1, v0
	v_mov_b32_e32 v0, v30
	v_pk_mul_f32 v[0:1], v[0:1], v[32:33]
	s_nop 0
	v_mul_f32_e32 v3, v0, v1
	v_mul_f32_e32 v0, 0xbfb8aa3b, v4
	v_exp_f32_e32 v0, v0
	v_mov_b32_e32 v33, v4
	v_add_f32_e32 v0, 1.0, v0
	v_rcp_f32_e32 v1, v0
	v_mov_b32_e32 v0, v31
	v_pk_mul_f32 v[0:1], v[0:1], v[32:33]
	s_nop 0
	v_mul_f32_e32 v0, v0, v1
	v_cvt_pk_bf16_f32 v0, v3, v0
	s_nop 0
	v_cndmask_b32_e32 v1, 0, v0, vcc
	v_cndmask_b32_e32 v0, 0, v2, vcc
	global_store_dwordx2 v[34:35], v[0:1], off offset:48
	v_mov_b32_e32 v0, v170
	v_mov_b32_e32 v1, v171
	v_lshlrev_b32_e32 v33, 16, v0
	v_and_b32_e32 v2, 0xffff0000, v0
	v_mul_f32_e32 v0, 0xbfb8aa3b, v33
	v_exp_f32_e32 v0, v0
	v_lshlrev_b32_e32 v3, 16, v1
	v_and_b32_e32 v4, 0xffff0000, v1
	v_add_f32_e32 v0, 1.0, v0
	v_rcp_f32_e32 v1, v0
	v_mov_b32_e32 v0, v12
	v_pk_mul_f32 v[0:1], v[0:1], v[32:33]
	s_nop 0
	v_mul_f32_e32 v5, v0, v1
	v_mul_f32_e32 v0, 0xbfb8aa3b, v2
	v_exp_f32_e32 v0, v0
	v_mov_b32_e32 v33, v2
	v_add_f32_e32 v0, 1.0, v0
	v_rcp_f32_e32 v1, v0
	v_mov_b32_e32 v0, v13
	v_pk_mul_f32 v[0:1], v[0:1], v[32:33]
	s_nop 0
	v_mul_f32_e32 v2, v0, v1
	v_mul_f32_e32 v0, 0xbfb8aa3b, v3
	v_exp_f32_e32 v0, v0
	v_mov_b32_e32 v33, v3
	v_cvt_pk_bf16_f32 v2, v5, v2
	v_add_f32_e32 v0, 1.0, v0
	v_rcp_f32_e32 v1, v0
	v_mov_b32_e32 v0, v14
	v_pk_mul_f32 v[0:1], v[0:1], v[32:33]
	s_nop 0
	v_mul_f32_e32 v3, v0, v1
	v_mul_f32_e32 v0, 0xbfb8aa3b, v4
	v_exp_f32_e32 v0, v0
	v_mov_b32_e32 v33, v4
	v_add_f32_e32 v0, 1.0, v0
	v_rcp_f32_e32 v1, v0
	v_mov_b32_e32 v0, v15
	v_pk_mul_f32 v[0:1], v[0:1], v[32:33]
	s_nop 0
	v_mul_f32_e32 v0, v0, v1
	v_cvt_pk_bf16_f32 v0, v3, v0
	s_nop 0
	v_cndmask_b32_e32 v1, 0, v0, vcc
	v_cndmask_b32_e32 v0, 0, v2, vcc
	global_store_dwordx2 v[34:35], v[0:1], off offset:112
